# baseline (speedup 1.0000x reference)
; __device__ __forceinline__ void ln_pass(int mode, bf16_t* X, bf16_t* U, const float* PART, int nparts, const float* g, const float* b, float* yout, float* mvout, int G, int bid, bool dry) {
;     ...
;         bf16_t* xr = X + (size_t)row * D;
;         float v[4][8];
;         if (row < MP || (mode == 0)) {
; #pragma unroll
;             for (int j = 0; j < 4; ++j) { const u32x4 w = *(const u32x4*)(xr + (j * 64 + lane) * 8);
;                 v[j][0] = bflo(w.x); v[j][1] = bfhi(w.x); v[j][2] = bflo(w.y); v[j][3] = bfhi(w.y); v[j][4] = bflo(w.z); v[j][5] = bfhi(w.z); v[j][6] = bflo(w.w); v[j][7] = bfhi(w.w); }
;         }
;         if (row >= MP) {
;             const int r = row - MP;
;             if (mode == 0) {
; #pragma unroll
;                 for (int j = 0; j < 4; ++j)
; #pragma unroll
;                     for (int e = 0; e < 8; ++e) v[j][e] *= ALPHA;
;                 for (int s = 0; s < nparts; ++s) { const float* pp = PART + ((size_t)s * 256 + r) * D;
; #pragma unroll
;                     for (int j = 0; j < 4; ++j) { const f32x4 a = __builtin_nontemporal_load((const f32x4*)(pp + (j * 64 + lane) * 8)), c = __builtin_nontemporal_load((const f32x4*)(pp + (j * 64 + lane) * 8 + 4));
; #pragma unroll
;                         for (int e = 0; e < 4; ++e) { v[j][e] += a[e]; v[j][4 + e] += c[e]; } } }
;             } else {
;                 float uu[4][8];
; #pragma unroll
;                 for (int j = 0; j < 4; ++j)
; #pragma unroll
;                     for (int e = 0; e < 8; ++e) { v[j][e] = 0.f; uu[j][e] = 0.f; }
;                 for (int s = 0; s < nparts; ++s) { const float* pp = PART + ((size_t)s * 256 + r) * 4096;
; #pragma unroll
;                     for (int j = 0; j < 4; ++j) { const f32x4 a = *(const f32x4*)(pp + (j * 64 + lane) * 8), c = *(const f32x4*)(pp + (j * 64 + lane) * 8 + 4);
;                         const f32x4 a2 = *(const f32x4*)(pp + 2048 + (j * 64 + lane) * 8), c2 = *(const f32x4*)(pp + 2048 + (j * 64 + lane) * 8 + 4);
; #pragma unroll
;                         for (int e = 0; e < 4; ++e) { uu[j][e] += a[e]; uu[j][4 + e] += c[e]; v[j][e] += a2[e]; v[j][4 + e] += c2[e]; } } }
; #pragma unroll
;                 for (int j = 0; j < 4; ++j) {
; #pragma unroll
;                     for (int e = 0; e < 8; ++e) { v[j][e] = gelu_t(v[j][e]); uu[j][e] = gelu_t(uu[j][e]); }
.LBB0_1205:
	v_mov_b32_e32 v108, 0x3727c5ac
	v_mov_b32_e32 v109, 0x260
	global_load_dwordx4 v[110:113], v[8:9], off
	global_load_dwordx4 v[114:117], v[8:9], off offset:16
	global_load_dwordx4 v[118:121], v[8:9], off offset:2048
	global_load_dwordx4 v[122:125], v[8:9], off offset:2064
	v_add_co_u32_e32 v208, vcc, 0x1000, v8
	s_nop 1
	v_addc_co_u32_e32 v209, vcc, 0, v9, vcc
	global_load_dwordx4 v[126:129], v[208:209], off
	global_load_dwordx4 v[130:133], v[208:209], off offset:16
	global_load_dwordx4 v[134:137], v[208:209], off offset:2048
	global_load_dwordx4 v[138:141], v[208:209], off offset:2064
	global_load_dwordx4 v[142:145], v[10:11], off
	global_load_dwordx4 v[146:149], v[10:11], off offset:16
	global_load_dwordx4 v[150:153], v[10:11], off offset:2048
	global_load_dwordx4 v[154:157], v[10:11], off offset:2064
	v_add_co_u32_e32 v208, vcc, 0x1000, v10
	s_nop 1
	v_addc_co_u32_e32 v209, vcc, 0, v11, vcc
	global_load_dwordx4 v[158:161], v[208:209], off
	global_load_dwordx4 v[162:165], v[208:209], off offset:16
	global_load_dwordx4 v[166:169], v[208:209], off offset:2048
	global_load_dwordx4 v[170:173], v[208:209], off offset:2064
	global_load_dwordx4 v[214:217], v[22:23], off offset:-2048
	global_load_dwordx4 v[218:221], v[22:23], off offset:-1024
	global_load_dwordx4 v[222:225], v[22:23], off
	global_load_dwordx4 v[226:229], v[22:23], off offset:1024
	s_waitcnt vmcnt(0)
	s_branch .Lmy_ln6_body
.Lmy_ln6_loop:
	s_waitcnt vmcnt(4)
.Lmy_ln6_body:
	v_lshlrev_b32_e32 v174, 16, v214
	v_and_b32_e32 v175, 0xffff0000, v214
	v_lshlrev_b32_e32 v176, 16, v215
	v_and_b32_e32 v177, 0xffff0000, v215
	v_lshlrev_b32_e32 v178, 16, v216
	v_and_b32_e32 v179, 0xffff0000, v216
	v_lshlrev_b32_e32 v180, 16, v217
	v_and_b32_e32 v181, 0xffff0000, v217
	v_lshlrev_b32_e32 v182, 16, v218
	v_and_b32_e32 v183, 0xffff0000, v218
	v_lshlrev_b32_e32 v184, 16, v219
	v_and_b32_e32 v185, 0xffff0000, v219
	v_lshlrev_b32_e32 v186, 16, v220
	v_and_b32_e32 v187, 0xffff0000, v220
	v_lshlrev_b32_e32 v188, 16, v221
	v_and_b32_e32 v189, 0xffff0000, v221
	v_lshlrev_b32_e32 v190, 16, v222
	v_and_b32_e32 v191, 0xffff0000, v222
	v_lshlrev_b32_e32 v192, 16, v223
	v_and_b32_e32 v193, 0xffff0000, v223
	v_lshlrev_b32_e32 v194, 16, v224
	v_and_b32_e32 v195, 0xffff0000, v224
	v_lshlrev_b32_e32 v196, 16, v225
	v_and_b32_e32 v197, 0xffff0000, v225
	v_lshlrev_b32_e32 v198, 16, v226
	v_and_b32_e32 v199, 0xffff0000, v226
	v_lshlrev_b32_e32 v200, 16, v227
	v_and_b32_e32 v201, 0xffff0000, v227
	v_lshlrev_b32_e32 v202, 16, v228
	v_and_b32_e32 v203, 0xffff0000, v228
	v_lshlrev_b32_e32 v204, 16, v229
	v_and_b32_e32 v205, 0xffff0000, v229
	v_mov_b32_e32 v206, v22
	v_mov_b32_e32 v207, v23
	s_cmp_lt_i32 s11, 0x4000
	s_cbranch_scc0 .Lmy_ln6_sample
	s_mov_b32 s6, s4
	s_add_i32 s6, s11, s6
	s_cmp_lt_i32 s6, 0x4100
	s_cbranch_scc0 .Lmy_ln6_compute
	v_lshl_add_u64 v[22:23], v[22:23], 0, s[8:9]
	global_load_dwordx4 v[214:217], v[22:23], off offset:-2048
	global_load_dwordx4 v[218:221], v[22:23], off offset:-1024
	global_load_dwordx4 v[222:225], v[22:23], off
	global_load_dwordx4 v[226:229], v[22:23], off offset:1024
.Lmy_ln6_compute:
	v_add_f32_e32 v245, 0, v174
	v_add_f32_e32 v245, v175, v245
	v_add_f32_e32 v245, v176, v245
	v_add_f32_e32 v245, v177, v245
	v_add_f32_e32 v245, v178, v245
	v_add_f32_e32 v245, v179, v245
	v_add_f32_e32 v245, v180, v245
	v_add_f32_e32 v245, v181, v245
	v_add_f32_e32 v245, v182, v245
	v_add_f32_e32 v245, v183, v245
	v_add_f32_e32 v245, v184, v245
	v_add_f32_e32 v245, v185, v245
	v_add_f32_e32 v245, v186, v245
	v_add_f32_e32 v245, v187, v245
	v_add_f32_e32 v245, v188, v245
	v_add_f32_e32 v245, v189, v245
	v_add_f32_e32 v245, v190, v245
	v_add_f32_e32 v245, v191, v245
	v_add_f32_e32 v245, v192, v245
	v_add_f32_e32 v245, v193, v245
	v_add_f32_e32 v245, v194, v245
	v_add_f32_e32 v245, v195, v245
	v_add_f32_e32 v245, v196, v245
	v_add_f32_e32 v245, v197, v245
	v_add_f32_e32 v245, v198, v245
	v_add_f32_e32 v245, v199, v245
	v_add_f32_e32 v245, v200, v245
	v_add_f32_e32 v245, v201, v245
	v_add_f32_e32 v245, v202, v245
	v_add_f32_e32 v245, v203, v245
	v_add_f32_e32 v245, v204, v245
	v_add_f32_e32 v245, v205, v245
	ds_bpermute_b32 v248, v56, v245
	s_waitcnt lgkmcnt(0)
	v_add_f32_e32 v245, v245, v248
	ds_bpermute_b32 v248, v57, v245
	s_waitcnt lgkmcnt(0)
	v_add_f32_e32 v245, v245, v248
	ds_bpermute_b32 v248, v58, v245
	s_waitcnt lgkmcnt(0)
	v_add_f32_e32 v245, v245, v248
	ds_bpermute_b32 v248, v59, v245
	s_waitcnt lgkmcnt(0)
	v_add_f32_e32 v245, v245, v248
	ds_bpermute_b32 v248, v60, v245
	s_waitcnt lgkmcnt(0)
	v_add_f32_e32 v245, v245, v248
	ds_bpermute_b32 v248, v61, v245
	s_waitcnt lgkmcnt(0)
; __device__ __forceinline__ unsigned cvt_pk(float lo, float hi) { unsigned r; asm("v_cvt_pk_bf16_f32 %0, %1, %2" : "=v"(r) : "v"(lo), "v"(hi)); return r; }
; __device__ __forceinline__ void ln_pass(int mode, bf16_t* X, bf16_t* U, const float* PART, int nparts, const float* g, const float* b, float* yout, float* mvout, int G, int bid, bool dry) {
;     ...
;         const float mean = wave_sum(sum) * (1.f / D);
;         float q = 0.f;
; #pragma unroll
;         for (int j = 0; j < 4; ++j)
; #pragma unroll
;             for (int e = 0; e < 8; ++e) { v[j][e] -= mean; q += v[j][e] * v[j][e]; }
;         const float rstd = 1.0f / sqrtf(wave_sum(q) * (1.f / D) + LN_EPS);
;         if (dry) continue;
; #pragma unroll
;         for (int j = 0; j < 4; ++j) {
;             const int c0 = (j * 64 + lane) * 8;
;             const f32x4 g0 = *(const f32x4*)(g + c0), g1 = *(const f32x4*)(g + c0 + 4), b0 = *(const f32x4*)(b + c0), b1 = *(const f32x4*)(b + c0 + 4);
;             f32x4 y0, y1;
; #pragma unroll
;             for (int e = 0; e < 4; ++e) { y0[e] = v[j][e] * rstd * g0[e] + b0[e]; y1[e] = v[j][4 + e] * rstd * g1[e] + b1[e]; }
;             if (yout) { __builtin_nontemporal_store(y0, (f32x4*)(yout + (size_t)row * D + c0)); __builtin_nontemporal_store(y1, (f32x4*)(yout + (size_t)row * D + c0 + 4)); }
;             else { u32x4 w; w.x = cvt_pk(y0[0], y0[1]); w.y = cvt_pk(y0[2], y0[3]); w.z = cvt_pk(y1[0], y1[1]); w.w = cvt_pk(y1[2], y1[3]); *(u32x4*)(xr + c0) = w; }
;             if (mvout && row >= MP) { *(f32x4*)(mvout + (size_t)(row - MP) * D + c0) = y0; *(f32x4*)(mvout + (size_t)(row - MP) * D + c0 + 4) = y1; }
;         }
	v_add_f32_e32 v245, v245, v248
	v_fmac_f32_e32 v174, 0xba000000, v245
	v_fmac_f32_e32 v175, 0xba000000, v245
	v_fmac_f32_e32 v176, 0xba000000, v245
	v_fmac_f32_e32 v177, 0xba000000, v245
	v_fmac_f32_e32 v178, 0xba000000, v245
	v_fmac_f32_e32 v179, 0xba000000, v245
	v_fmac_f32_e32 v180, 0xba000000, v245
	v_fmac_f32_e32 v181, 0xba000000, v245
	v_fmac_f32_e32 v182, 0xba000000, v245
	v_fmac_f32_e32 v183, 0xba000000, v245
	v_fmac_f32_e32 v184, 0xba000000, v245
	v_fmac_f32_e32 v185, 0xba000000, v245
	v_fmac_f32_e32 v186, 0xba000000, v245
	v_fmac_f32_e32 v187, 0xba000000, v245
	v_fmac_f32_e32 v188, 0xba000000, v245
	v_fmac_f32_e32 v189, 0xba000000, v245
	v_fmac_f32_e32 v190, 0xba000000, v245
	v_fmac_f32_e32 v191, 0xba000000, v245
	v_fmac_f32_e32 v192, 0xba000000, v245
	v_fmac_f32_e32 v193, 0xba000000, v245
	v_fmac_f32_e32 v194, 0xba000000, v245
	v_fmac_f32_e32 v195, 0xba000000, v245
	v_fmac_f32_e32 v196, 0xba000000, v245
	v_fmac_f32_e32 v197, 0xba000000, v245
	v_fmac_f32_e32 v198, 0xba000000, v245
	v_fmac_f32_e32 v199, 0xba000000, v245
	v_fmac_f32_e32 v200, 0xba000000, v245
	v_fmac_f32_e32 v201, 0xba000000, v245
	v_fmac_f32_e32 v202, 0xba000000, v245
	v_fmac_f32_e32 v203, 0xba000000, v245
	v_fmac_f32_e32 v204, 0xba000000, v245
	v_fmac_f32_e32 v205, 0xba000000, v245
	v_mul_f32_e32 v249, v175, v175
	v_fmac_f32_e32 v249, v174, v174
	v_fmac_f32_e32 v249, v176, v176
	v_fmac_f32_e32 v249, v177, v177
	v_fmac_f32_e32 v249, v178, v178
	v_fmac_f32_e32 v249, v179, v179
	v_fmac_f32_e32 v249, v180, v180
	v_fmac_f32_e32 v249, v181, v181
	v_fmac_f32_e32 v249, v182, v182
	v_fmac_f32_e32 v249, v183, v183
	v_fmac_f32_e32 v249, v184, v184
	v_fmac_f32_e32 v249, v185, v185
	v_fmac_f32_e32 v249, v186, v186
	v_fmac_f32_e32 v249, v187, v187
	v_fmac_f32_e32 v249, v188, v188
	v_fmac_f32_e32 v249, v189, v189
	v_fmac_f32_e32 v249, v190, v190
	v_fmac_f32_e32 v249, v191, v191
	v_fmac_f32_e32 v249, v192, v192
	v_fmac_f32_e32 v249, v193, v193
	v_fmac_f32_e32 v249, v194, v194
	v_fmac_f32_e32 v249, v195, v195
	v_fmac_f32_e32 v249, v196, v196
	v_fmac_f32_e32 v249, v197, v197
	v_fmac_f32_e32 v249, v198, v198
	v_fmac_f32_e32 v249, v199, v199
	v_fmac_f32_e32 v249, v200, v200
	v_fmac_f32_e32 v249, v201, v201
	v_fmac_f32_e32 v249, v202, v202
	v_fmac_f32_e32 v249, v203, v203
	v_fmac_f32_e32 v249, v204, v204
	v_fmac_f32_e32 v249, v205, v205
	ds_bpermute_b32 v248, v56, v249
	s_waitcnt lgkmcnt(0)
	v_add_f32_e32 v249, v249, v248
	ds_bpermute_b32 v248, v57, v249
	s_waitcnt lgkmcnt(0)
	v_add_f32_e32 v249, v249, v248
	ds_bpermute_b32 v248, v58, v249
	s_waitcnt lgkmcnt(0)
	v_add_f32_e32 v249, v249, v248
	ds_bpermute_b32 v248, v59, v249
	s_waitcnt lgkmcnt(0)
	v_add_f32_e32 v249, v249, v248
	ds_bpermute_b32 v248, v60, v249
	s_waitcnt lgkmcnt(0)
	v_add_f32_e32 v249, v249, v248
	ds_bpermute_b32 v248, v61, v249
	s_waitcnt lgkmcnt(0)
	v_add_f32_e32 v249, v249, v248
	v_fmamk_f32 v238, v249, 0x3a000000, v108
	v_cmp_gt_f32_e32 vcc, 0xf800000, v238
	v_mul_f32_e32 v239, 0x4f800000, v238
	s_nop 0
	v_cndmask_b32_e32 v238, v238, v239, vcc
	v_sqrt_f32_e32 v239, v238
	s_nop 0
	v_add_u32_e32 v240, -1, v239
	v_fma_f32 v241, -v240, v239, v238
	v_cmp_ge_f32_e64 s[0:1], 0, v241
	v_add_u32_e32 v241, 1, v239
	s_nop 0
	v_cndmask_b32_e64 v240, v239, v240, s[0:1]
	v_fma_f32 v239, -v241, v239, v238
	v_cmp_lt_f32_e64 s[0:1], 0, v239
	s_nop 1
	v_cndmask_b32_e64 v239, v240, v241, s[0:1]
	v_mul_f32_e32 v240, 0x37800000, v239
	v_cndmask_b32_e32 v239, v239, v240, vcc
	v_cmp_class_f32_e32 vcc, v238, v109
	s_nop 1
	v_cndmask_b32_e32 v238, v239, v238, vcc
	v_div_scale_f32 v239, s[0:1], v238, v238, 1.0
	v_rcp_f32_e32 v240, v239
	s_nop 0
	v_fma_f32 v241, -v239, v240, 1.0
	v_fmac_f32_e32 v240, v241, v240
	v_div_scale_f32 v241, vcc, 1.0, v238, 1.0
	v_mul_f32_e32 v242, v241, v240
	v_fma_f32 v243, -v239, v242, v241
	v_fmac_f32_e32 v242, v243, v240
	v_fma_f32 v239, -v239, v242, v241
	v_div_fmas_f32 v239, v239, v240, v242
	v_div_fixup_f32 v238, v239, v238, 1.0
	v_mul_f32_e32 v174, v174, v238
	v_fma_f32 v174, v110, v174, v142
	v_mul_f32_e32 v175, v175, v238
	v_fma_f32 v175, v111, v175, v143
	v_mul_f32_e32 v176, v176, v238
	v_fma_f32 v176, v112, v176, v144
	v_mul_f32_e32 v177, v177, v238
	v_fma_f32 v177, v113, v177, v145
	v_mul_f32_e32 v178, v178, v238
	v_fma_f32 v178, v114, v178, v146
	v_mul_f32_e32 v179, v179, v238
	v_fma_f32 v179, v115, v179, v147
	v_mul_f32_e32 v180, v180, v238
	v_fma_f32 v180, v116, v180, v148
	v_mul_f32_e32 v181, v181, v238
	v_fma_f32 v181, v117, v181, v149
	v_cvt_pk_bf16_f32 v230, v174, v175
	v_cvt_pk_bf16_f32 v231, v176, v177
	v_cvt_pk_bf16_f32 v232, v178, v179
	v_cvt_pk_bf16_f32 v233, v180, v181
	global_store_dwordx4 v[206:207], v[230:233], off offset:-2048
	v_mul_f32_e32 v182, v182, v238
	v_fma_f32 v182, v118, v182, v150
	v_mul_f32_e32 v183, v183, v238
	v_fma_f32 v183, v119, v183, v151
	v_mul_f32_e32 v184, v184, v238
	v_fma_f32 v184, v120, v184, v152
	v_mul_f32_e32 v185, v185, v238
	v_fma_f32 v185, v121, v185, v153
	v_mul_f32_e32 v186, v186, v238
	v_fma_f32 v186, v122, v186, v154
	v_mul_f32_e32 v187, v187, v238
	v_fma_f32 v187, v123, v187, v155
	v_mul_f32_e32 v188, v188, v238
	v_fma_f32 v188, v124, v188, v156
	v_mul_f32_e32 v189, v189, v238
	v_fma_f32 v189, v125, v189, v157
	v_cvt_pk_bf16_f32 v234, v182, v183
	v_cvt_pk_bf16_f32 v235, v184, v185
	v_cvt_pk_bf16_f32 v236, v186, v187
	v_cvt_pk_bf16_f32 v237, v188, v189
	global_store_dwordx4 v[206:207], v[234:237], off offset:-1024
	v_mul_f32_e32 v190, v190, v238
	v_fma_f32 v190, v126, v190, v158
	v_mul_f32_e32 v191, v191, v238
	v_fma_f32 v191, v127, v191, v159
	v_mul_f32_e32 v192, v192, v238
	v_fma_f32 v192, v128, v192, v160
	v_mul_f32_e32 v193, v193, v238
	v_fma_f32 v193, v129, v193, v161
	v_mul_f32_e32 v194, v194, v238
	v_fma_f32 v194, v130, v194, v162
	v_mul_f32_e32 v195, v195, v238
	v_fma_f32 v195, v131, v195, v163
	v_mul_f32_e32 v196, v196, v238
	v_fma_f32 v196, v132, v196, v164
	v_mul_f32_e32 v197, v197, v238
	v_fma_f32 v197, v133, v197, v165
	v_cvt_pk_bf16_f32 v230, v190, v191
	v_cvt_pk_bf16_f32 v231, v192, v193
	v_cvt_pk_bf16_f32 v232, v194, v195
	v_cvt_pk_bf16_f32 v233, v196, v197
	global_store_dwordx4 v[206:207], v[230:233], off
	v_mul_f32_e32 v198, v198, v238
	v_fma_f32 v198, v134, v198, v166
	v_mul_f32_e32 v199, v199, v238
	v_fma_f32 v199, v135, v199, v167
	v_mul_f32_e32 v200, v200, v238
	v_fma_f32 v200, v136, v200, v168
	v_mul_f32_e32 v201, v201, v238
	v_fma_f32 v201, v137, v201, v169
	v_mul_f32_e32 v202, v202, v238
	v_fma_f32 v202, v138, v202, v170
	v_mul_f32_e32 v203, v203, v238
	v_fma_f32 v203, v139, v203, v171
	v_mul_f32_e32 v204, v204, v238
	v_fma_f32 v204, v140, v204, v172
	v_mul_f32_e32 v205, v205, v238
	v_fma_f32 v205, v141, v205, v173
	v_cvt_pk_bf16_f32 v234, v198, v199
	v_cvt_pk_bf16_f32 v235, v200, v201
	v_cvt_pk_bf16_f32 v236, v202, v203
	v_cvt_pk_bf16_f32 v237, v204, v205
	global_store_dwordx4 v[206:207], v[234:237], off offset:1024
	s_mov_b32 s6, s4
	s_add_i32 s11, s11, s6
	s_cmp_lt_i32 s11, 0x4100
	s_cbranch_scc1 .Lmy_ln6_loop
	s_branch .LBB0_1207
; __device__ __forceinline__ void ln_pass(int mode, bf16_t* X, bf16_t* U, const float* PART, int nparts, const float* g, const float* b, float* yout, float* mvout, int G, int bid, bool dry) {
;     ...
;         if (row >= MP) {
;             const int r = row - MP;
;             if (mode == 0) {
; #pragma unroll
;                 for (int j = 0; j < 4; ++j)
; #pragma unroll
;                     for (int e = 0; e < 8; ++e) v[j][e] *= ALPHA;
;                 for (int s = 0; s < nparts; ++s) { const float* pp = PART + ((size_t)s * 256 + r) * D;
; #pragma unroll
;                     for (int j = 0; j < 4; ++j) { const f32x4 a = __builtin_nontemporal_load((const f32x4*)(pp + (j * 64 + lane) * 8)), c = __builtin_nontemporal_load((const f32x4*)(pp + (j * 64 + lane) * 8 + 4));
; #pragma unroll
;                         for (int e = 0; e < 4; ++e) { v[j][e] += a[e]; v[j][4 + e] += c[e]; } } }
.Lmy_ln6_sample:
	s_add_i32 s6, s11, 0xffffc000
	s_lshl_b32 s0, s6, 13
	s_mov_b32 s1, 0
	v_lshl_add_u64 v[208:209], v[20:21], 0, s[0:1]
	s_mov_b32 s0, 0x3fb504f3
	v_add_co_u32_e32 v246, vcc, 0x1000, v208
	s_nop 1
	v_addc_co_u32_e32 v247, vcc, 0, v209, vcc
	global_load_dwordx4 v[0:3], v[208:209], off nt
	global_load_dwordx4 v[4:7], v[208:209], off offset:16 nt
	global_load_dwordx4 v[24:27], v[208:209], off offset:2048 nt
	global_load_dwordx4 v[28:31], v[208:209], off offset:2064 nt
	global_load_dwordx4 v[32:35], v[246:247], off nt
	global_load_dwordx4 v[36:39], v[246:247], off offset:16 nt
	global_load_dwordx4 v[40:43], v[246:247], off offset:2048 nt
	global_load_dwordx4 v[44:47], v[246:247], off offset:2064 nt
	v_add_co_u32_e32 v208, vcc, 0x200000, v208
	s_nop 1
	v_addc_co_u32_e32 v209, vcc, 0, v209, vcc
	v_add_co_u32_e32 v246, vcc, 0x1000, v208
	s_nop 1
	v_addc_co_u32_e32 v247, vcc, 0, v209, vcc
	global_load_dwordx4 v[48:51], v[208:209], off nt
	global_load_dwordx4 v[52:55], v[208:209], off offset:16 nt
	global_load_dwordx4 v[64:67], v[208:209], off offset:2048 nt
	global_load_dwordx4 v[68:71], v[208:209], off offset:2064 nt
	global_load_dwordx4 v[72:75], v[246:247], off nt
	global_load_dwordx4 v[76:79], v[246:247], off offset:16 nt
	global_load_dwordx4 v[80:83], v[246:247], off offset:2048 nt
	global_load_dwordx4 v[84:87], v[246:247], off offset:2064 nt
	v_add_co_u32_e32 v208, vcc, 0x200000, v208
	s_nop 1
	v_addc_co_u32_e32 v209, vcc, 0, v209, vcc
	s_waitcnt vmcnt(8)
	v_pk_fma_f32 v[174:175], v[174:175], s[0:1], v[0:1] op_sel_hi:[1,0,1]
	v_pk_fma_f32 v[176:177], v[176:177], s[0:1], v[2:3] op_sel_hi:[1,0,1]
	v_pk_fma_f32 v[178:179], v[178:179], s[0:1], v[4:5] op_sel_hi:[1,0,1]
	v_pk_fma_f32 v[180:181], v[180:181], s[0:1], v[6:7] op_sel_hi:[1,0,1]
	v_pk_fma_f32 v[182:183], v[182:183], s[0:1], v[24:25] op_sel_hi:[1,0,1]
	v_pk_fma_f32 v[184:185], v[184:185], s[0:1], v[26:27] op_sel_hi:[1,0,1]
	v_pk_fma_f32 v[186:187], v[186:187], s[0:1], v[28:29] op_sel_hi:[1,0,1]
	v_pk_fma_f32 v[188:189], v[188:189], s[0:1], v[30:31] op_sel_hi:[1,0,1]
	v_pk_fma_f32 v[190:191], v[190:191], s[0:1], v[32:33] op_sel_hi:[1,0,1]
	v_pk_fma_f32 v[192:193], v[192:193], s[0:1], v[34:35] op_sel_hi:[1,0,1]
	v_pk_fma_f32 v[194:195], v[194:195], s[0:1], v[36:37] op_sel_hi:[1,0,1]
	v_pk_fma_f32 v[196:197], v[196:197], s[0:1], v[38:39] op_sel_hi:[1,0,1]
	v_pk_fma_f32 v[198:199], v[198:199], s[0:1], v[40:41] op_sel_hi:[1,0,1]
	v_pk_fma_f32 v[200:201], v[200:201], s[0:1], v[42:43] op_sel_hi:[1,0,1]
	v_pk_fma_f32 v[202:203], v[202:203], s[0:1], v[44:45] op_sel_hi:[1,0,1]
	v_pk_fma_f32 v[204:205], v[204:205], s[0:1], v[46:47] op_sel_hi:[1,0,1]
	v_add_co_u32_e32 v246, vcc, 0x1000, v208
	s_nop 1
	v_addc_co_u32_e32 v247, vcc, 0, v209, vcc
	global_load_dwordx4 v[0:3], v[208:209], off nt
	global_load_dwordx4 v[4:7], v[208:209], off offset:16 nt
	global_load_dwordx4 v[24:27], v[208:209], off offset:2048 nt
	global_load_dwordx4 v[28:31], v[208:209], off offset:2064 nt
	global_load_dwordx4 v[32:35], v[246:247], off nt
	global_load_dwordx4 v[36:39], v[246:247], off offset:16 nt
	global_load_dwordx4 v[40:43], v[246:247], off offset:2048 nt
	global_load_dwordx4 v[44:47], v[246:247], off offset:2064 nt
	v_add_co_u32_e32 v208, vcc, 0x200000, v208
	s_nop 1
	v_addc_co_u32_e32 v209, vcc, 0, v209, vcc
	s_waitcnt vmcnt(8)
	v_pk_add_f32 v[174:175], v[174:175], v[48:49]
	v_pk_add_f32 v[176:177], v[176:177], v[50:51]
	v_pk_add_f32 v[178:179], v[178:179], v[52:53]
	v_pk_add_f32 v[180:181], v[180:181], v[54:55]
	v_pk_add_f32 v[182:183], v[182:183], v[64:65]
	v_pk_add_f32 v[184:185], v[184:185], v[66:67]
	v_pk_add_f32 v[186:187], v[186:187], v[68:69]
	v_pk_add_f32 v[188:189], v[188:189], v[70:71]
	v_pk_add_f32 v[190:191], v[190:191], v[72:73]
	v_pk_add_f32 v[192:193], v[192:193], v[74:75]
	v_pk_add_f32 v[194:195], v[194:195], v[76:77]
	v_pk_add_f32 v[196:197], v[196:197], v[78:79]
	v_pk_add_f32 v[198:199], v[198:199], v[80:81]
	v_pk_add_f32 v[200:201], v[200:201], v[82:83]
	v_pk_add_f32 v[202:203], v[202:203], v[84:85]
	v_pk_add_f32 v[204:205], v[204:205], v[86:87]
	v_add_co_u32_e32 v246, vcc, 0x1000, v208
	s_nop 1
	v_addc_co_u32_e32 v247, vcc, 0, v209, vcc
	global_load_dwordx4 v[48:51], v[208:209], off nt
	global_load_dwordx4 v[52:55], v[208:209], off offset:16 nt
	global_load_dwordx4 v[64:67], v[208:209], off offset:2048 nt
	global_load_dwordx4 v[68:71], v[208:209], off offset:2064 nt
	global_load_dwordx4 v[72:75], v[246:247], off nt
	global_load_dwordx4 v[76:79], v[246:247], off offset:16 nt
	global_load_dwordx4 v[80:83], v[246:247], off offset:2048 nt
	global_load_dwordx4 v[84:87], v[246:247], off offset:2064 nt
	v_add_co_u32_e32 v208, vcc, 0x200000, v208
	s_nop 1
	v_addc_co_u32_e32 v209, vcc, 0, v209, vcc
	s_waitcnt vmcnt(8)
	v_pk_add_f32 v[174:175], v[174:175], v[0:1]
	v_pk_add_f32 v[176:177], v[176:177], v[2:3]
	v_pk_add_f32 v[178:179], v[178:179], v[4:5]
	v_pk_add_f32 v[180:181], v[180:181], v[6:7]
	v_pk_add_f32 v[182:183], v[182:183], v[24:25]
	v_pk_add_f32 v[184:185], v[184:185], v[26:27]
	v_pk_add_f32 v[186:187], v[186:187], v[28:29]
	v_pk_add_f32 v[188:189], v[188:189], v[30:31]
	v_pk_add_f32 v[190:191], v[190:191], v[32:33]
	v_pk_add_f32 v[192:193], v[192:193], v[34:35]
	v_pk_add_f32 v[194:195], v[194:195], v[36:37]
	v_pk_add_f32 v[196:197], v[196:197], v[38:39]
	v_pk_add_f32 v[198:199], v[198:199], v[40:41]
	v_pk_add_f32 v[200:201], v[200:201], v[42:43]
	v_pk_add_f32 v[202:203], v[202:203], v[44:45]
	v_pk_add_f32 v[204:205], v[204:205], v[46:47]
	v_add_co_u32_e32 v246, vcc, 0x1000, v208
	s_nop 1
	v_addc_co_u32_e32 v247, vcc, 0, v209, vcc
	global_load_dwordx4 v[0:3], v[208:209], off nt
	global_load_dwordx4 v[4:7], v[208:209], off offset:16 nt
	global_load_dwordx4 v[24:27], v[208:209], off offset:2048 nt
	global_load_dwordx4 v[28:31], v[208:209], off offset:2064 nt
	global_load_dwordx4 v[32:35], v[246:247], off nt
	global_load_dwordx4 v[36:39], v[246:247], off offset:16 nt
	global_load_dwordx4 v[40:43], v[246:247], off offset:2048 nt
	global_load_dwordx4 v[44:47], v[246:247], off offset:2064 nt
	v_add_co_u32_e32 v208, vcc, 0x200000, v208
	s_nop 1
	v_addc_co_u32_e32 v209, vcc, 0, v209, vcc
	s_waitcnt vmcnt(8)
; __device__ __forceinline__ void ln_pass(int mode, bf16_t* X, bf16_t* U, const float* PART, int nparts, const float* g, const float* b, float* yout, float* mvout, int G, int bid, bool dry) {
;     ...
;                 for (int s = 0; s < nparts; ++s) { const float* pp = PART + ((size_t)s * 256 + r) * D;
; #pragma unroll
;                     for (int j = 0; j < 4; ++j) { const f32x4 a = __builtin_nontemporal_load((const f32x4*)(pp + (j * 64 + lane) * 8)), c = __builtin_nontemporal_load((const f32x4*)(pp + (j * 64 + lane) * 8 + 4));
; #pragma unroll
;                         for (int e = 0; e < 4; ++e) { v[j][e] += a[e]; v[j][4 + e] += c[e]; } } }
	v_pk_add_f32 v[174:175], v[174:175], v[48:49]
	v_pk_add_f32 v[176:177], v[176:177], v[50:51]
	v_pk_add_f32 v[178:179], v[178:179], v[52:53]
	v_pk_add_f32 v[180:181], v[180:181], v[54:55]
	v_pk_add_f32 v[182:183], v[182:183], v[64:65]
	v_pk_add_f32 v[184:185], v[184:185], v[66:67]
	v_pk_add_f32 v[186:187], v[186:187], v[68:69]
	v_pk_add_f32 v[188:189], v[188:189], v[70:71]
	v_pk_add_f32 v[190:191], v[190:191], v[72:73]
	v_pk_add_f32 v[192:193], v[192:193], v[74:75]
	v_pk_add_f32 v[194:195], v[194:195], v[76:77]
	v_pk_add_f32 v[196:197], v[196:197], v[78:79]
	v_pk_add_f32 v[198:199], v[198:199], v[80:81]
	v_pk_add_f32 v[200:201], v[200:201], v[82:83]
	v_pk_add_f32 v[202:203], v[202:203], v[84:85]
	v_pk_add_f32 v[204:205], v[204:205], v[86:87]
	v_add_co_u32_e32 v246, vcc, 0x1000, v208
	s_nop 1
	v_addc_co_u32_e32 v247, vcc, 0, v209, vcc
	global_load_dwordx4 v[48:51], v[208:209], off nt
	global_load_dwordx4 v[52:55], v[208:209], off offset:16 nt
	global_load_dwordx4 v[64:67], v[208:209], off offset:2048 nt
	global_load_dwordx4 v[68:71], v[208:209], off offset:2064 nt
	global_load_dwordx4 v[72:75], v[246:247], off nt
	global_load_dwordx4 v[76:79], v[246:247], off offset:16 nt
	global_load_dwordx4 v[80:83], v[246:247], off offset:2048 nt
	global_load_dwordx4 v[84:87], v[246:247], off offset:2064 nt
	v_add_co_u32_e32 v208, vcc, 0x200000, v208
	s_nop 1
	v_addc_co_u32_e32 v209, vcc, 0, v209, vcc
	s_waitcnt vmcnt(8)
	v_pk_add_f32 v[174:175], v[174:175], v[0:1]
	v_pk_add_f32 v[176:177], v[176:177], v[2:3]
	v_pk_add_f32 v[178:179], v[178:179], v[4:5]
	v_pk_add_f32 v[180:181], v[180:181], v[6:7]
	v_pk_add_f32 v[182:183], v[182:183], v[24:25]
	v_pk_add_f32 v[184:185], v[184:185], v[26:27]
	v_pk_add_f32 v[186:187], v[186:187], v[28:29]
	v_pk_add_f32 v[188:189], v[188:189], v[30:31]
	v_pk_add_f32 v[190:191], v[190:191], v[32:33]
	v_pk_add_f32 v[192:193], v[192:193], v[34:35]
	v_pk_add_f32 v[194:195], v[194:195], v[36:37]
	v_pk_add_f32 v[196:197], v[196:197], v[38:39]
	v_pk_add_f32 v[198:199], v[198:199], v[40:41]
	v_pk_add_f32 v[200:201], v[200:201], v[42:43]
	v_pk_add_f32 v[202:203], v[202:203], v[44:45]
	v_pk_add_f32 v[204:205], v[204:205], v[46:47]
	v_add_co_u32_e32 v246, vcc, 0x1000, v208
	s_nop 1
	v_addc_co_u32_e32 v247, vcc, 0, v209, vcc
	global_load_dwordx4 v[0:3], v[208:209], off nt
	global_load_dwordx4 v[4:7], v[208:209], off offset:16 nt
	global_load_dwordx4 v[24:27], v[208:209], off offset:2048 nt
	global_load_dwordx4 v[28:31], v[208:209], off offset:2064 nt
	global_load_dwordx4 v[32:35], v[246:247], off nt
	global_load_dwordx4 v[36:39], v[246:247], off offset:16 nt
	global_load_dwordx4 v[40:43], v[246:247], off offset:2048 nt
	global_load_dwordx4 v[44:47], v[246:247], off offset:2064 nt
	v_add_co_u32_e32 v208, vcc, 0x200000, v208
	s_nop 1
	v_addc_co_u32_e32 v209, vcc, 0, v209, vcc
	s_waitcnt vmcnt(8)
	v_pk_add_f32 v[174:175], v[174:175], v[48:49]
	v_pk_add_f32 v[176:177], v[176:177], v[50:51]
	v_pk_add_f32 v[178:179], v[178:179], v[52:53]
	v_pk_add_f32 v[180:181], v[180:181], v[54:55]
	v_pk_add_f32 v[182:183], v[182:183], v[64:65]
	v_pk_add_f32 v[184:185], v[184:185], v[66:67]
	v_pk_add_f32 v[186:187], v[186:187], v[68:69]
	v_pk_add_f32 v[188:189], v[188:189], v[70:71]
	v_pk_add_f32 v[190:191], v[190:191], v[72:73]
	v_pk_add_f32 v[192:193], v[192:193], v[74:75]
	v_pk_add_f32 v[194:195], v[194:195], v[76:77]
	v_pk_add_f32 v[196:197], v[196:197], v[78:79]
	v_pk_add_f32 v[198:199], v[198:199], v[80:81]
	v_pk_add_f32 v[200:201], v[200:201], v[82:83]
	v_pk_add_f32 v[202:203], v[202:203], v[84:85]
	v_pk_add_f32 v[204:205], v[204:205], v[86:87]
	v_add_co_u32_e32 v246, vcc, 0x1000, v208
	s_nop 1
	v_addc_co_u32_e32 v247, vcc, 0, v209, vcc
	global_load_dwordx4 v[48:51], v[208:209], off nt
	global_load_dwordx4 v[52:55], v[208:209], off offset:16 nt
	global_load_dwordx4 v[64:67], v[208:209], off offset:2048 nt
	global_load_dwordx4 v[68:71], v[208:209], off offset:2064 nt
	global_load_dwordx4 v[72:75], v[246:247], off nt
	global_load_dwordx4 v[76:79], v[246:247], off offset:16 nt
	global_load_dwordx4 v[80:83], v[246:247], off offset:2048 nt
	global_load_dwordx4 v[84:87], v[246:247], off offset:2064 nt
	v_add_co_u32_e32 v208, vcc, 0x200000, v208
	s_nop 1
	v_addc_co_u32_e32 v209, vcc, 0, v209, vcc
	s_waitcnt vmcnt(8)
	v_pk_add_f32 v[174:175], v[174:175], v[0:1]
	v_pk_add_f32 v[176:177], v[176:177], v[2:3]
	v_pk_add_f32 v[178:179], v[178:179], v[4:5]
	v_pk_add_f32 v[180:181], v[180:181], v[6:7]
	v_pk_add_f32 v[182:183], v[182:183], v[24:25]
	v_pk_add_f32 v[184:185], v[184:185], v[26:27]
	v_pk_add_f32 v[186:187], v[186:187], v[28:29]
	v_pk_add_f32 v[188:189], v[188:189], v[30:31]
	v_pk_add_f32 v[190:191], v[190:191], v[32:33]
	v_pk_add_f32 v[192:193], v[192:193], v[34:35]
	v_pk_add_f32 v[194:195], v[194:195], v[36:37]
	v_pk_add_f32 v[196:197], v[196:197], v[38:39]
	v_pk_add_f32 v[198:199], v[198:199], v[40:41]
	v_pk_add_f32 v[200:201], v[200:201], v[42:43]
	v_pk_add_f32 v[202:203], v[202:203], v[44:45]
	v_pk_add_f32 v[204:205], v[204:205], v[46:47]
	s_waitcnt vmcnt(0)
	v_pk_add_f32 v[174:175], v[174:175], v[48:49]
	v_pk_add_f32 v[176:177], v[176:177], v[50:51]
	v_pk_add_f32 v[178:179], v[178:179], v[52:53]
	v_pk_add_f32 v[180:181], v[180:181], v[54:55]
	v_pk_add_f32 v[182:183], v[182:183], v[64:65]
	v_pk_add_f32 v[184:185], v[184:185], v[66:67]
	v_pk_add_f32 v[186:187], v[186:187], v[68:69]
	v_pk_add_f32 v[188:189], v[188:189], v[70:71]
	v_pk_add_f32 v[190:191], v[190:191], v[72:73]
	v_pk_add_f32 v[192:193], v[192:193], v[74:75]
	v_pk_add_f32 v[194:195], v[194:195], v[76:77]
	v_pk_add_f32 v[196:197], v[196:197], v[78:79]
	v_pk_add_f32 v[198:199], v[198:199], v[80:81]
	v_pk_add_f32 v[200:201], v[200:201], v[82:83]
	v_pk_add_f32 v[202:203], v[202:203], v[84:85]
	v_pk_add_f32 v[204:205], v[204:205], v[86:87]
	s_branch .Lmy_ln6_compute
